# attention loop: barrier at loop head, next-tile scalar setup computed inside PV MFMA gaps, LDS fragment reads issued as early as registers allow, near-band bias added by VALU out of line
# speedup vs baseline: 1.0372x; 1.0158x over previous
; #define PG8_WAIT_V(n) asm volatile("s_waitcnt vmcnt(" #n ")" ::: "memory")
; #define PG8_WAIT_L(n) asm volatile("s_waitcnt lgkmcnt(" #n ")" ::: "memory")
; #define PG8_BAR __builtin_amdgcn_s_barrier()
; #define ATT_STAGE(t, ring) do { const int _so = (int)((size_t)(t) * inc); _Pragma("unroll") for (int _i = 0; _i < 4; ++_i) \
;     __builtin_amdgcn_raw_ptr_buffer_load_lds(srs, (LAS void*)(lds + stg_base + (ring) * 16384 + _i * 1024), 16, (int)soff[_i & 1], _so + (int)(_i * cstride), 0, 0); } while (0)
; #define ATT_LDK(ring) do { _Pragma("unroll") for (int kh = 0; kh < 2; ++kh) _Pragma("unroll") for (int ks = 0; ks < 4; ++ks) \
;     kf[kh][ks] = *(const LAS bf16x8*)(lds + (ring) * 16384 + kh * 4096 + koff[ks]); } while (0)
; DI void attn_item(const Params& p, const int item) {
;     ...
;   PG8_WAIT_L(0); PG8_BAR;
;   if (wid < 4) ATT_STAGE(3, 0);
;   ATT_SM(0, pf); ATT_SM(1, pf);
;   if (wid < 4) PG8_WAIT_V(8);
;   PG8_BAR;
;   ATT_LDK(1);
;   int m0 = 0, m1 = 1, m2 = 2;
;   for (int t = 0; t < nT - 1; ++t) {
;     PG8_WAIT_L(0); PG8_WAIT_V(4); PG8_BAR;
;     { const int tk = t + 4 < nT ? t + 4 : nT - 1, tv = t + 2 < nT ? t + 2 : nT - 1; if (wid < 4) ATT_STAGE(tk, m1); else ATT_STAGE(tv, m2); }
.LBB0_986:
	s_nop 4
	v_exp_f32_e32 v0, v0
	v_exp_f32_e32 v1, v1
	v_exp_f32_e32 v2, v2
	v_exp_f32_e32 v3, v3
	v_exp_f32_e32 v4, v4
	v_cvt_pk_bf16_f32 v120, v0, v1
	v_add_f32_e32 v0, 0, v0
	v_exp_f32_e32 v5, v5
	v_add_f32_e32 v0, v1, v0
	v_exp_f32_e32 v6, v6
	v_add_f32_e32 v0, v2, v0
	v_exp_f32_e32 v7, v7
	v_add_f32_e32 v0, v3, v0
	v_exp_f32_e32 v8, v8
	v_add_f32_e32 v0, v4, v0
	v_exp_f32_e32 v9, v9
	v_add_f32_e32 v0, v5, v0
	v_exp_f32_e32 v10, v10
	v_add_f32_e32 v0, v6, v0
	v_exp_f32_e32 v11, v11
	v_add_f32_e32 v0, v7, v0
	v_exp_f32_e32 v12, v12
	v_add_f32_e32 v0, v8, v0
	v_exp_f32_e32 v13, v13
	v_add_f32_e32 v0, v9, v0
	v_exp_f32_e32 v14, v14
	v_add_f32_e32 v0, v10, v0
	v_exp_f32_e32 v15, v15
	v_add_f32_e32 v0, v11, v0
	v_exp_f32_e32 v16, v16
	v_add_f32_e32 v0, v12, v0
	v_exp_f32_e32 v17, v17
	v_add_f32_e32 v0, v13, v0
	v_exp_f32_e32 v18, v18
	v_add_f32_e32 v0, v14, v0
	v_exp_f32_e32 v19, v19
	v_add_f32_e32 v0, v15, v0
	v_exp_f32_e32 v20, v20
	v_add_f32_e32 v0, v16, v0
	v_exp_f32_e32 v21, v21
	v_add_f32_e32 v0, v17, v0
	v_exp_f32_e32 v22, v22
	v_add_f32_e32 v0, v18, v0
	v_exp_f32_e32 v23, v23
	v_add_f32_e32 v0, v19, v0
	v_exp_f32_e32 v24, v24
	v_add_f32_e32 v0, v20, v0
	v_exp_f32_e32 v25, v25
	v_add_f32_e32 v0, v21, v0
	v_exp_f32_e32 v26, v26
	v_add_f32_e32 v0, v22, v0
	v_exp_f32_e32 v27, v27
	v_add_f32_e32 v0, v23, v0
	v_exp_f32_e32 v28, v28
	v_add_f32_e32 v0, v24, v0
	v_exp_f32_e32 v29, v29
	v_add_f32_e32 v0, v25, v0
	v_exp_f32_e32 v30, v30
	v_add_f32_e32 v0, v26, v0
	v_exp_f32_e32 v31, v31
	v_add_f32_e32 v0, v27, v0
	s_barrier
	ds_read_b128 v[128:131], v74 offset:20480
	ds_read_b128 v[132:135], v74 offset:16384
	ds_read_b128 v[136:139], v71 offset:20480
	ds_read_b128 v[140:143], v71 offset:16384
	ds_read_b128 v[144:147], v69 offset:20480
	ds_read_b128 v[148:151], v69 offset:16384
	ds_read_b128 v[156:159], v68 offset:20480
	ds_read_b128 v[152:155], v68 offset:16384
	v_add_f32_e32 v0, v28, v0
	v_add_f32_e32 v0, v29, v0
	v_add_f32_e32 v0, v30, v0
	v_add_f32_e32 v231, v31, v0
	v_sub_f32_e32 v0, v64, v66
	v_mul_f32_e32 v0, 0x3fb8aa3b, v0
	v_sub_f32_e32 v1, v65, v66
	v_exp_f32_e32 v229, v0
	v_mul_f32_e32 v0, 0xbfb8aa3b, v1
	v_exp_f32_e32 v230, v0
	v_cvt_pk_bf16_f32 v121, v2, v3
	v_cvt_pk_bf16_f32 v122, v4, v5
	v_cvt_pk_bf16_f32 v123, v6, v7
	v_lshlrev_b32_e32 v2, 7, v201
	v_bitop3_b32 v3, v217, v67, 7 bitop3:0x78
	v_bitop3_b32 v4, v70, v67, 7 bitop3:0x78
	v_bitop3_b32 v5, v72, v67, 7 bitop3:0x78
	v_bitop3_b32 v6, v73, v67, 7 bitop3:0x78
	v_mov_b32_e32 v48, v193
	v_mov_b32_e32 v49, v193
	v_cvt_pk_bf16_f32 v112, v8, v9
	v_cvt_pk_bf16_f32 v113, v10, v11
	v_cvt_pk_bf16_f32 v114, v12, v13
	v_cvt_pk_bf16_f32 v115, v14, v15
	v_cvt_pk_bf16_f32 v124, v16, v17
	v_cvt_pk_bf16_f32 v125, v18, v19
	v_cvt_pk_bf16_f32 v126, v20, v21
	v_cvt_pk_bf16_f32 v127, v22, v23
	v_cvt_pk_bf16_f32 v116, v24, v25
	v_cvt_pk_bf16_f32 v117, v26, v27
	v_cvt_pk_bf16_f32 v118, v28, v29
	v_cvt_pk_bf16_f32 v119, v30, v31
	s_add_i32 s5, s22, 0x100
	s_lshr_b32 s20, s20, 6
	v_lshl_or_b32 v228, v3, 4, v2
	v_lshl_or_b32 v227, v4, 4, v2
	v_lshl_or_b32 v226, v5, 4, v2
	v_lshl_or_b32 v225, v6, 4, v2
	v_mov_b32_e32 v50, v193
	v_mov_b32_e32 v51, v193
	v_mov_b32_e32 v52, v193
	v_mov_b32_e32 v53, v193
	v_mov_b32_e32 v54, v193
	v_mov_b32_e32 v55, v193
	v_mov_b32_e32 v56, v193
	v_mov_b32_e32 v57, v193
	v_mov_b32_e32 v58, v193
	v_mov_b32_e32 v59, v193
	v_mov_b32_e32 v60, v193
	v_mov_b32_e32 v61, v193
	v_mov_b32_e32 v62, v193
	v_mov_b32_e32 v63, v193
	v_mov_b64_e32 v[32:33], v[48:49]
	v_mov_b64_e32 v[16:17], v[48:49]
	v_mov_b64_e32 v[0:1], v[48:49]
	s_lshr_b32 s21, s5, 6
	s_add_i32 s20, s20, -1
	s_addk_i32 s22, 0xc0
	s_add_i32 s23, s19, -1
	s_mov_b32 s25, 1
	s_mov_b32 s24, 0
	v_mov_b64_e32 v[34:35], v[50:51]
	v_mov_b64_e32 v[36:37], v[52:53]
	v_mov_b64_e32 v[38:39], v[54:55]
	v_mov_b64_e32 v[40:41], v[56:57]
	v_mov_b64_e32 v[42:43], v[58:59]
	v_mov_b64_e32 v[44:45], v[60:61]
	v_mov_b64_e32 v[46:47], v[62:63]
	v_mov_b64_e32 v[18:19], v[50:51]
	v_mov_b64_e32 v[20:21], v[52:53]
	v_mov_b64_e32 v[22:23], v[54:55]
	v_mov_b64_e32 v[24:25], v[56:57]
	v_mov_b64_e32 v[26:27], v[58:59]
	v_mov_b64_e32 v[28:29], v[60:61]
	v_mov_b64_e32 v[30:31], v[62:63]
	v_mov_b64_e32 v[2:3], v[50:51]
	v_mov_b64_e32 v[4:5], v[52:53]
	v_mov_b64_e32 v[6:7], v[54:55]
	v_mov_b64_e32 v[8:9], v[56:57]
	v_mov_b64_e32 v[10:11], v[58:59]
	v_mov_b64_e32 v[12:13], v[60:61]
	v_mov_b64_e32 v[14:15], v[62:63]
	s_mov_b32 s28, 0
	s_mov_b32 s26, 0
	s_mov_b32 s27, 1
	s_mov_b32 s25, 2
	s_and_b64 s[0:1], s[8:9], exec
	s_cselect_b32 s0, s27, s25
	s_add_i32 s1, s4, s28
	s_lshl_b32 s0, s0, 14
	s_min_u32 s1, s1, s20
	s_add_i32 s98, s18, s0
	s_mul_i32 s99, s1, s17
	s_lshl_b32 s1, s26, 14
	v_add_u32_e32 v241, s1, v228
	v_add_u32_e32 v242, s1, v227
	v_add_u32_e32 v234, s1, v226
	v_add_u32_e32 v235, s1, v225
	s_add_i32 s29, s28, 1
	s_cmp_lt_i32 s29, s19
	s_cselect_b64 s[34:35], -1, 0
	s_cmp_ge_u32 s29, s21
	s_cselect_b64 s[30:31], -1, 0
	s_or_b64 s[34:35], s[34:35], s[30:31]
	s_cmp_eq_u32 s19, s28
	s_cselect_b64 s[0:1], -1, 0
	s_and_b64 s[30:31], s[10:11], s[0:1]
	s_cmp_eq_u32 s5, s24
	s_cselect_b64 s[0:1], -1, 0
	s_or_b64 s[30:31], s[30:31], s[0:1]
	s_cmp_eq_u32 s22, s24
	s_cselect_b64 s[100:101], -1, 0
	s_lshl_b32 s1, s25, 14
	v_add_u32_e32 v237, s1, v220
	v_add_u32_e32 v238, s1, v221
	v_add_u32_e32 v239, s1, v222
	v_add_u32_e32 v240, s1, v223
.LBB0_987:
	s_waitcnt lgkmcnt(0)
	s_waitcnt vmcnt(4)
	s_barrier
	v_mfma_f32_32x32x16_bf16 v[64:79], v[152:155], v[96:99], 0
	ds_read_b128 v[176:179], v241 offset:49152
	ds_read_b128 v[180:183], v241 offset:53248
	v_mfma_f32_32x32x16_bf16 v[80:95], v[156:159], v[96:99], 0
	ds_read_b128 v[172:175], v242 offset:49152
	ds_read_b128 v[168:171], v242 offset:53248
	s_and_b64 vcc, exec, s[30:31]
	s_cbranch_vccnz .Latt_rescale
; #define LAS __attribute__((address_space(3)))
; #define PG8_WAIT_V(n) asm volatile("s_waitcnt vmcnt(" #n ")" ::: "memory")
; #define PG8_WAIT_L(n) asm volatile("s_waitcnt lgkmcnt(" #n ")" ::: "memory")
; #define PG8_BAR __builtin_amdgcn_s_barrier()
; #define PG8_SCHED __builtin_amdgcn_sched_barrier(0)
; #define MFMA32(a, b, c) __builtin_amdgcn_mfma_f32_32x32x16_bf16((a), (b), (c), 0, 0, 0)
; #define ATT_STAGE(t, ring) do { const int _so = (int)((size_t)(t) * inc); _Pragma("unroll") for (int _i = 0; _i < 4; ++_i) \
;     __builtin_amdgcn_raw_ptr_buffer_load_lds(srs, (LAS void*)(lds + stg_base + (ring) * 16384 + _i * 1024), 16, (int)soff[_i & 1], _so + (int)(_i * cstride), 0, 0); } while (0)
; DI void attn_item(const Params& p, const int item) {
;     ...
;     PG8_WAIT_L(0); PG8_WAIT_V(4); PG8_BAR;
;     { const int tk = t + 4 < nT ? t + 4 : nT - 1, tv = t + 2 < nT ? t + 2 : nT - 1; if (wid < 4) ATT_STAGE(tk, m1); else ATT_STAGE(tv, m2); }
;     const LAS unsigned char* vb = lds + m0 * 16384;
;     if ((t == tL && tL > 0) || t == tR) {
;       const float f = t == tR ? fR : fL;
; #pragma unroll
;       for (int db = 0; db < 4; ++db)
; #pragma unroll
;         for (int i = 0; i < 16; ++i) O[db][i] *= f;
;     }
;     bf16x8 vfA[4][2], vfB[4][2];
; #pragma unroll
;     for (int db = 0; db < 4; ++db)
; #pragma unroll
;       for (int s = 0; s < 2; ++s) vfA[db][s] = *(const LAS bf16x8*)(vb + db * 4096 + voff[s]);
;     ATT_QK(t + 1);
;     PG8_SCHED;
; #pragma unroll
;     for (int db = 0; db < 4; ++db)
; #pragma unroll
;       for (int s = 0; s < 2; ++s) vfB[db][s] = *(const LAS bf16x8*)(vb + db * 4096 + voff[s + 2]);
;     bf16x8 pfN[4];
; #pragma unroll
;     for (int s = 0; s < 2; ++s)
; #pragma unroll
;       for (int db = 0; db < 4; ++db) O[db] = MFMA32(vfA[db][s], pf[s], O[db]);
;     ATT_SM(0, pfN);
;     PG8_SCHED;
;     ATT_LDK(m2);
; #pragma unroll
;     for (int s = 0; s < 2; ++s)
; #pragma unroll
;       for (int db = 0; db < 4; ++db) O[db] = MFMA32(vfB[db][s], pf[s + 2], O[db]);
;     ATT_SM(1, pfN);
;     PG8_SCHED;
; #pragma unroll
;     for (int s = 0; s < 4; ++s) pf[s] = pfN[s];
;     { const int mm = m0; m0 = m1; m1 = m2; m2 = mm; }
.Latt_rescale_done:
	s_cmp_eq_u32 s23, s28
	s_cselect_b64 vcc, -1, 0
	s_mov_b32 m0, s98
	v_mfma_f32_32x32x16_bf16 v[64:79], v[148:151], v[100:103], v[64:79]
	buffer_load_dwordx4 v218, s[64:67], s99 offen lds
	ds_read_b128 v[184:187], v241 offset:57344
	ds_read_b128 v[188:191], v241 offset:61440
	v_mfma_f32_32x32x16_bf16 v[80:95], v[144:147], v[100:103], v[80:95]
	s_add_i32 m0, s98, 0x400
	s_add_i32 s99, s99, s7
	buffer_load_dwordx4 v219, s[64:67], s99 offen lds
	ds_read_b128 v[164:167], v242 offset:57344
	ds_read_b128 v[160:163], v242 offset:61440
	v_mfma_f32_32x32x16_bf16 v[64:79], v[140:143], v[104:107], v[64:79]
	ds_read_b128 v[152:155], v237
	ds_read_b128 v[156:159], v237 offset:4096
	v_mfma_f32_32x32x16_bf16 v[80:95], v[136:139], v[104:107], v[80:95]
	s_add_i32 m0, s98, 0x800
	s_add_i32 s99, s99, s7
	buffer_load_dwordx4 v218, s[64:67], s99 offen lds
	ds_read_b128 v[148:151], v238
	ds_read_b128 v[144:147], v238 offset:4096
	v_mfma_f32_32x32x16_bf16 v[64:79], v[132:135], v[108:111], v[64:79]
	v_mul_f32_e32 v233, v229, v231
	v_cndmask_b32_e32 v231, v231, v233, vcc
	v_mul_f32_e32 v233, v230, v231
	v_cndmask_b32_e64 v231, v231, v233, s[100:101]
	v_mfma_f32_32x32x16_bf16 v[80:95], v[128:131], v[108:111], v[80:95]
	s_add_i32 m0, s98, 0xc00
	s_add_i32 s99, s99, s7
	buffer_load_dwordx4 v219, s[64:67], s99 offen lds
	ds_read_b128 v[128:131], v234 offset:49152
	ds_read_b128 v[132:135], v234 offset:53248
	ds_read_b128 v[136:139], v234 offset:57344
	ds_read_b128 v[140:143], v234 offset:61440
	s_andn2_b64 vcc, exec, s[34:35]
	s_cbranch_vccnz .Latt_near
.Latt_near_done:
	s_waitcnt lgkmcnt(15)
	v_mfma_f32_32x32x16_bf16 v[48:63], v[176:179], v[120:123], v[48:63]
	s_nop 1
	v_exp_f32_e32 v64, v64
	v_exp_f32_e32 v65, v65
	v_exp_f32_e32 v66, v66
	v_exp_f32_e32 v67, v67
	s_waitcnt lgkmcnt(14)
	v_mfma_f32_32x32x16_bf16 v[32:47], v[180:183], v[120:123], v[32:47]
	ds_read_b128 v[176:179], v235 offset:49152
	ds_read_b128 v[180:183], v235 offset:53248
	v_exp_f32_e32 v68, v68
	v_exp_f32_e32 v69, v69
	v_add_f32_e32 v231, v64, v231
	v_add_f32_e32 v231, v65, v231
	v_add_f32_e32 v231, v66, v231
	s_waitcnt lgkmcnt(13)
	v_mfma_f32_32x32x16_bf16 v[16:31], v[184:187], v[120:123], v[16:31]
	ds_read_b128 v[184:187], v235 offset:61440
	v_exp_f32_e32 v70, v70
	v_exp_f32_e32 v71, v71
	v_add_f32_e32 v231, v67, v231
	v_add_f32_e32 v231, v68, v231
	v_add_f32_e32 v231, v69, v231
	s_waitcnt lgkmcnt(13)
	v_mfma_f32_32x32x16_bf16 v[0:15], v[188:191], v[120:123], v[0:15]
	v_exp_f32_e32 v72, v72
	v_exp_f32_e32 v73, v73
	v_add_f32_e32 v231, v70, v231
	v_add_f32_e32 v231, v71, v231
	v_cvt_pk_bf16_f32 v120, v64, v65
	v_mfma_f32_32x32x16_bf16 v[48:63], v[172:175], v[112:115], v[48:63]
	ds_read_b128 v[172:175], v235 offset:57344
	v_exp_f32_e32 v74, v74
	v_exp_f32_e32 v75, v75
	v_add_f32_e32 v231, v72, v231
	v_add_f32_e32 v231, v73, v231
	v_cvt_pk_bf16_f32 v121, v66, v67
	v_mfma_f32_32x32x16_bf16 v[32:47], v[168:171], v[112:115], v[32:47]
	v_exp_f32_e32 v76, v76
	v_exp_f32_e32 v77, v77
	v_add_f32_e32 v231, v74, v231
	v_add_f32_e32 v231, v75, v231
	v_cvt_pk_bf16_f32 v122, v68, v69
	s_waitcnt lgkmcnt(13)
	v_mfma_f32_32x32x16_bf16 v[16:31], v[164:167], v[112:115], v[16:31]
	v_exp_f32_e32 v78, v78
	v_exp_f32_e32 v79, v79
	v_add_f32_e32 v231, v76, v231
	v_add_f32_e32 v231, v77, v231
	v_cvt_pk_bf16_f32 v123, v70, v71
	s_waitcnt lgkmcnt(12)
	v_mfma_f32_32x32x16_bf16 v[0:15], v[160:163], v[112:115], v[0:15]
	v_exp_f32_e32 v80, v80
	v_exp_f32_e32 v81, v81
	v_add_f32_e32 v231, v78, v231
	v_add_f32_e32 v231, v79, v231
	v_cvt_pk_bf16_f32 v112, v72, v73
	s_waitcnt lgkmcnt(7)
	v_mfma_f32_32x32x16_bf16 v[48:63], v[128:131], v[124:127], v[48:63]
	ds_read_b128 v[128:131], v240 offset:4096
	s_mov_b32 s1, s26
	s_mov_b32 s26, s27
	s_mov_b32 s27, s25
	s_mov_b32 s25, s1
	s_add_i32 s28, s28, 1
	s_add_i32 s24, s24, 64
	v_exp_f32_e32 v82, v82
	v_exp_f32_e32 v83, v83
	v_add_f32_e32 v231, v80, v231
	v_add_f32_e32 v231, v81, v231
	v_cvt_pk_bf16_f32 v113, v74, v75
	s_waitcnt lgkmcnt(7)
	v_mfma_f32_32x32x16_bf16 v[32:47], v[132:135], v[124:127], v[32:47]
	ds_read_b128 v[132:135], v240
	s_and_b64 s[0:1], s[8:9], exec
	s_cselect_b32 s0, s27, s25
	s_add_i32 s1, s4, s28
	s_lshl_b32 s0, s0, 14
	v_exp_f32_e32 v84, v84
	v_exp_f32_e32 v85, v85
	v_add_f32_e32 v231, v82, v231
	v_add_f32_e32 v231, v83, v231
	v_cvt_pk_bf16_f32 v114, v76, v77
	s_waitcnt lgkmcnt(7)
	v_mfma_f32_32x32x16_bf16 v[16:31], v[136:139], v[124:127], v[16:31]
	ds_read_b128 v[136:139], v239 offset:4096
	s_min_u32 s1, s1, s20
	s_add_i32 s98, s18, s0
	s_mul_i32 s99, s1, s17
	s_lshl_b32 s1, s26, 14
	v_exp_f32_e32 v86, v86
	v_exp_f32_e32 v87, v87
	v_add_f32_e32 v231, v84, v231
	v_add_f32_e32 v231, v85, v231
	v_cvt_pk_bf16_f32 v115, v78, v79
	s_waitcnt lgkmcnt(7)
	v_mfma_f32_32x32x16_bf16 v[0:15], v[140:143], v[124:127], v[0:15]
	ds_read_b128 v[140:143], v239
	v_add_u32_e32 v241, s1, v228
	v_add_u32_e32 v242, s1, v227
	v_add_u32_e32 v234, s1, v226
	v_add_u32_e32 v235, s1, v225
	v_exp_f32_e32 v88, v88
	v_exp_f32_e32 v89, v89
	v_add_f32_e32 v231, v86, v231
	v_add_f32_e32 v231, v87, v231
	v_cvt_pk_bf16_f32 v124, v80, v81
	s_waitcnt lgkmcnt(7)
	v_mfma_f32_32x32x16_bf16 v[48:63], v[176:179], v[116:119], v[48:63]
	s_add_i32 s29, s28, 1
	s_cmp_lt_i32 s29, s19
	s_cselect_b64 s[34:35], -1, 0
	s_cmp_ge_u32 s29, s21
	s_cselect_b64 s[30:31], -1, 0
	s_or_b64 s[34:35], s[34:35], s[30:31]
	s_lshl_b32 s1, s25, 14
	v_add_u32_e32 v237, s1, v220
	v_add_u32_e32 v238, s1, v221
	v_add_u32_e32 v239, s1, v222
	v_add_u32_e32 v240, s1, v223
	v_exp_f32_e32 v90, v90
	v_exp_f32_e32 v91, v91
	v_add_f32_e32 v231, v88, v231
	v_add_f32_e32 v231, v89, v231
	v_cvt_pk_bf16_f32 v125, v82, v83
	s_waitcnt lgkmcnt(6)
	v_mfma_f32_32x32x16_bf16 v[32:47], v[180:183], v[116:119], v[32:47]
	s_cmp_eq_u32 s19, s28
	s_cselect_b64 s[0:1], -1, 0
	s_and_b64 s[30:31], s[10:11], s[0:1]
	s_cmp_eq_u32 s5, s24
	s_cselect_b64 s[0:1], -1, 0
	s_or_b64 s[30:31], s[30:31], s[0:1]
	v_exp_f32_e32 v92, v92
	v_exp_f32_e32 v93, v93
	v_add_f32_e32 v231, v90, v231
	v_add_f32_e32 v231, v91, v231
	v_cvt_pk_bf16_f32 v126, v84, v85
	s_waitcnt lgkmcnt(4)
	v_mfma_f32_32x32x16_bf16 v[16:31], v[172:175], v[116:119], v[16:31]
	s_cmp_eq_u32 s22, s24
	s_cselect_b64 s[100:101], -1, 0
	v_exp_f32_e32 v94, v94
	v_exp_f32_e32 v95, v95
	v_add_f32_e32 v231, v92, v231
	v_add_f32_e32 v231, v93, v231
	v_cvt_pk_bf16_f32 v127, v86, v87
	v_mfma_f32_32x32x16_bf16 v[0:15], v[184:187], v[116:119], v[0:15]
	v_add_f32_e32 v231, v94, v231
	v_add_f32_e32 v231, v95, v231
	v_cvt_pk_bf16_f32 v116, v88, v89
	v_cvt_pk_bf16_f32 v117, v90, v91
	v_cvt_pk_bf16_f32 v118, v92, v93
	v_cvt_pk_bf16_f32 v119, v94, v95
	s_cmp_eq_u32 s20, s28
	s_cbranch_scc0 .LBB0_987
	s_branch .LBB0_995
; DI void attn_item(const Params& p, const int item) {
;     ...
;     if ((t == tL && tL > 0) || t == tR) {
;       const float f = t == tR ? fR : fL;
; #pragma unroll
;       for (int db = 0; db < 4; ++db)
; #pragma unroll
;         for (int i = 0; i < 16; ++i) O[db][i] *= f;
.Latt_rescale:
	v_cndmask_b32_e64 v232, v229, v230, s[0:1]
	v_pk_mul_f32 v[62:63], v[62:63], v[232:233] op_sel_hi:[1,0]
	v_pk_mul_f32 v[60:61], v[60:61], v[232:233] op_sel_hi:[1,0]
	v_pk_mul_f32 v[58:59], v[58:59], v[232:233] op_sel_hi:[1,0]
	v_pk_mul_f32 v[56:57], v[56:57], v[232:233] op_sel_hi:[1,0]
	v_pk_mul_f32 v[54:55], v[54:55], v[232:233] op_sel_hi:[1,0]
	v_pk_mul_f32 v[52:53], v[52:53], v[232:233] op_sel_hi:[1,0]
	v_pk_mul_f32 v[50:51], v[50:51], v[232:233] op_sel_hi:[1,0]
	v_pk_mul_f32 v[48:49], v[48:49], v[232:233] op_sel_hi:[1,0]
	v_pk_mul_f32 v[46:47], v[46:47], v[232:233] op_sel_hi:[1,0]
	v_pk_mul_f32 v[44:45], v[44:45], v[232:233] op_sel_hi:[1,0]
	v_pk_mul_f32 v[42:43], v[42:43], v[232:233] op_sel_hi:[1,0]
	v_pk_mul_f32 v[40:41], v[40:41], v[232:233] op_sel_hi:[1,0]
	v_pk_mul_f32 v[38:39], v[38:39], v[232:233] op_sel_hi:[1,0]
	v_pk_mul_f32 v[36:37], v[36:37], v[232:233] op_sel_hi:[1,0]
	v_pk_mul_f32 v[34:35], v[34:35], v[232:233] op_sel_hi:[1,0]
	v_pk_mul_f32 v[32:33], v[32:33], v[232:233] op_sel_hi:[1,0]
	v_pk_mul_f32 v[30:31], v[30:31], v[232:233] op_sel_hi:[1,0]
	v_pk_mul_f32 v[28:29], v[28:29], v[232:233] op_sel_hi:[1,0]
	v_pk_mul_f32 v[26:27], v[26:27], v[232:233] op_sel_hi:[1,0]
	v_pk_mul_f32 v[24:25], v[24:25], v[232:233] op_sel_hi:[1,0]
	v_pk_mul_f32 v[22:23], v[22:23], v[232:233] op_sel_hi:[1,0]
	v_pk_mul_f32 v[20:21], v[20:21], v[232:233] op_sel_hi:[1,0]
	v_pk_mul_f32 v[18:19], v[18:19], v[232:233] op_sel_hi:[1,0]
	v_pk_mul_f32 v[16:17], v[16:17], v[232:233] op_sel_hi:[1,0]
	v_pk_mul_f32 v[14:15], v[14:15], v[232:233] op_sel_hi:[1,0]
	v_pk_mul_f32 v[12:13], v[12:13], v[232:233] op_sel_hi:[1,0]
	v_pk_mul_f32 v[10:11], v[10:11], v[232:233] op_sel_hi:[1,0]
	v_pk_mul_f32 v[8:9], v[8:9], v[232:233] op_sel_hi:[1,0]
	v_pk_mul_f32 v[6:7], v[6:7], v[232:233] op_sel_hi:[1,0]
	v_pk_mul_f32 v[4:5], v[4:5], v[232:233] op_sel_hi:[1,0]
	v_pk_mul_f32 v[2:3], v[2:3], v[232:233] op_sel_hi:[1,0]
	v_pk_mul_f32 v[0:1], v[0:1], v[232:233] op_sel_hi:[1,0]
	s_branch .Latt_rescale_done
.Latt_near:
	v_add_u32_e32 v232, s24, v224
	s_add_i32 s0, 0, 0x20000
	v_add_u32_e32 v244, 0x40, v232
	v_add_u32_e32 v245, 0x41, v232
	v_add_u32_e32 v246, 0x42, v232
	v_add_u32_e32 v247, 0x43, v232
	v_add_u32_e32 v248, 0x44, v232
	v_add_u32_e32 v249, 0x45, v232
	v_add_u32_e32 v250, 0x46, v232
	v_add_u32_e32 v251, 0x47, v232
	v_med3_i32 v244, v244, s87, v216
	v_med3_i32 v245, v245, s87, v216
	v_med3_i32 v246, v246, s87, v216
	v_med3_i32 v247, v247, s87, v216
	v_med3_i32 v248, v248, s87, v216
	v_med3_i32 v249, v249, s87, v216
	v_med3_i32 v250, v250, s87, v216
	v_med3_i32 v251, v251, s87, v216
	v_lshl_add_u32 v244, v244, 2, s0
	v_lshl_add_u32 v245, v245, 2, s0
	v_lshl_add_u32 v246, v246, 2, s0
	v_lshl_add_u32 v247, v247, 2, s0
	v_lshl_add_u32 v248, v248, 2, s0
	v_lshl_add_u32 v249, v249, 2, s0
	v_lshl_add_u32 v250, v250, 2, s0
	v_lshl_add_u32 v251, v251, 2, s0
	ds_read_b32 v244, v244 offset:512
	ds_read_b32 v245, v245 offset:512
	ds_read_b32 v246, v246 offset:512
	ds_read_b32 v247, v247 offset:512
	ds_read_b32 v248, v248 offset:512
	ds_read_b32 v249, v249 offset:512
	ds_read_b32 v250, v250 offset:512
	ds_read_b32 v251, v251 offset:512
	s_waitcnt lgkmcnt(0)
	v_add_f32_e32 v64, v64, v244
	v_add_f32_e32 v65, v65, v245
	v_add_f32_e32 v66, v66, v246
	v_add_f32_e32 v67, v67, v247
	v_add_f32_e32 v68, v68, v248
	v_add_f32_e32 v69, v69, v249
	v_add_f32_e32 v70, v70, v250
	v_add_f32_e32 v71, v71, v251
	v_add_u32_e32 v244, 0x50, v232
	v_add_u32_e32 v245, 0x51, v232
	v_add_u32_e32 v246, 0x52, v232
	v_add_u32_e32 v247, 0x53, v232
	v_add_u32_e32 v248, 0x54, v232
	v_add_u32_e32 v249, 0x55, v232
	v_add_u32_e32 v250, 0x56, v232
	v_add_u32_e32 v251, 0x57, v232
	v_med3_i32 v244, v244, s87, v216
	v_med3_i32 v245, v245, s87, v216
	v_med3_i32 v246, v246, s87, v216
	v_med3_i32 v247, v247, s87, v216
	v_med3_i32 v248, v248, s87, v216
	v_med3_i32 v249, v249, s87, v216
	v_med3_i32 v250, v250, s87, v216
	v_med3_i32 v251, v251, s87, v216
	v_lshl_add_u32 v244, v244, 2, s0
	v_lshl_add_u32 v245, v245, 2, s0
	v_lshl_add_u32 v246, v246, 2, s0
	v_lshl_add_u32 v247, v247, 2, s0
	v_lshl_add_u32 v248, v248, 2, s0
	v_lshl_add_u32 v249, v249, 2, s0
	v_lshl_add_u32 v250, v250, 2, s0
	v_lshl_add_u32 v251, v251, 2, s0
	ds_read_b32 v244, v244 offset:512
	ds_read_b32 v245, v245 offset:512
	ds_read_b32 v246, v246 offset:512
	ds_read_b32 v247, v247 offset:512
	ds_read_b32 v248, v248 offset:512
	ds_read_b32 v249, v249 offset:512
	ds_read_b32 v250, v250 offset:512
	ds_read_b32 v251, v251 offset:512
	s_waitcnt lgkmcnt(0)
	v_add_f32_e32 v72, v72, v244
	v_add_f32_e32 v73, v73, v245
	v_add_f32_e32 v74, v74, v246
	v_add_f32_e32 v75, v75, v247
	v_add_f32_e32 v76, v76, v248
	v_add_f32_e32 v77, v77, v249
	v_add_f32_e32 v78, v78, v250
	v_add_f32_e32 v79, v79, v251
	v_add_u32_e32 v244, 0x60, v232
	v_add_u32_e32 v245, 0x61, v232
	v_add_u32_e32 v246, 0x62, v232
	v_add_u32_e32 v247, 0x63, v232
	v_add_u32_e32 v248, 0x64, v232
	v_add_u32_e32 v249, 0x65, v232
	v_add_u32_e32 v250, 0x66, v232
	v_add_u32_e32 v251, 0x67, v232
	v_med3_i32 v244, v244, s87, v216
	v_med3_i32 v245, v245, s87, v216
	v_med3_i32 v246, v246, s87, v216
	v_med3_i32 v247, v247, s87, v216
	v_med3_i32 v248, v248, s87, v216
	v_med3_i32 v249, v249, s87, v216
	v_med3_i32 v250, v250, s87, v216
	v_med3_i32 v251, v251, s87, v216
	v_lshl_add_u32 v244, v244, 2, s0
	v_lshl_add_u32 v245, v245, 2, s0
	v_lshl_add_u32 v246, v246, 2, s0
	v_lshl_add_u32 v247, v247, 2, s0
	v_lshl_add_u32 v248, v248, 2, s0
	v_lshl_add_u32 v249, v249, 2, s0
	v_lshl_add_u32 v250, v250, 2, s0
	v_lshl_add_u32 v251, v251, 2, s0
	ds_read_b32 v244, v244 offset:512
	ds_read_b32 v245, v245 offset:512
	ds_read_b32 v246, v246 offset:512
	ds_read_b32 v247, v247 offset:512
	ds_read_b32 v248, v248 offset:512
	ds_read_b32 v249, v249 offset:512
	ds_read_b32 v250, v250 offset:512
	ds_read_b32 v251, v251 offset:512
	s_waitcnt lgkmcnt(0)
	v_add_f32_e32 v80, v80, v244
	v_add_f32_e32 v81, v81, v245
	v_add_f32_e32 v82, v82, v246
	v_add_f32_e32 v83, v83, v247
	v_add_f32_e32 v84, v84, v248
	v_add_f32_e32 v85, v85, v249
	v_add_f32_e32 v86, v86, v250
	v_add_f32_e32 v87, v87, v251
	v_add_u32_e32 v244, 0x70, v232
	v_add_u32_e32 v245, 0x71, v232
	v_add_u32_e32 v246, 0x72, v232
	v_add_u32_e32 v247, 0x73, v232
	v_add_u32_e32 v248, 0x74, v232
	v_add_u32_e32 v249, 0x75, v232
	v_add_u32_e32 v250, 0x76, v232
	v_add_u32_e32 v251, 0x77, v232
	v_med3_i32 v244, v244, s87, v216
	v_med3_i32 v245, v245, s87, v216
	v_med3_i32 v246, v246, s87, v216
	v_med3_i32 v247, v247, s87, v216
	v_med3_i32 v248, v248, s87, v216
	v_med3_i32 v249, v249, s87, v216
	v_med3_i32 v250, v250, s87, v216
	v_med3_i32 v251, v251, s87, v216
	v_lshl_add_u32 v244, v244, 2, s0
	v_lshl_add_u32 v245, v245, 2, s0
	v_lshl_add_u32 v246, v246, 2, s0
	v_lshl_add_u32 v247, v247, 2, s0
	v_lshl_add_u32 v248, v248, 2, s0
	v_lshl_add_u32 v249, v249, 2, s0
	v_lshl_add_u32 v250, v250, 2, s0
	v_lshl_add_u32 v251, v251, 2, s0
	ds_read_b32 v244, v244 offset:512
	ds_read_b32 v245, v245 offset:512
	ds_read_b32 v246, v246 offset:512
	ds_read_b32 v247, v247 offset:512
	ds_read_b32 v248, v248 offset:512
	ds_read_b32 v249, v249 offset:512
	ds_read_b32 v250, v250 offset:512
	ds_read_b32 v251, v251 offset:512
	s_waitcnt lgkmcnt(0)
	v_add_f32_e32 v88, v88, v244
	v_add_f32_e32 v89, v89, v245
	v_add_f32_e32 v90, v90, v246
	v_add_f32_e32 v91, v91, v247
	v_add_f32_e32 v92, v92, v248
	v_add_f32_e32 v93, v93, v249
	v_add_f32_e32 v94, v94, v250
	v_add_f32_e32 v95, v95, v251
	s_branch .Latt_near_done
; #define LAS __attribute__((address_space(3)))
; #define PG8_WAIT_V(n) asm volatile("s_waitcnt vmcnt(" #n ")" ::: "memory")
; #define PG8_BAR __builtin_amdgcn_s_barrier()
; #define MFMA32(a, b, c) __builtin_amdgcn_mfma_f32_32x32x16_bf16((a), (b), (c), 0, 0, 0)
; DI void attn_item(const Params& p, const int item) {
;     ...
;   PG8_WAIT_V(0); PG8_BAR;
;   {
;     const LAS unsigned char* vb = lds + m0 * 16384;
;     if ((nT - 1 == tL && tL > 0) || nT - 1 == tR) {
;       const float f = nT - 1 == tR ? fR : fL;
; #pragma unroll
;       for (int db = 0; db < 4; ++db)
; #pragma unroll
;         for (int i = 0; i < 16; ++i) O[db][i] *= f;
;     }
; #pragma unroll
;     for (int db = 0; db < 4; ++db)
; #pragma unroll
;       for (int s = 0; s < 4; ++s) { const bf16x8 vf = *(const LAS bf16x8*)(vb + db * 4096 + voff[s]); O[db] = MFMA32(vf, pf[s], O[db]); }
;   }
;     ...
;   PG8_WAIT_V(0); PG8_BAR;
;   lsum += __shfl_xor(lsum, 32);
;   const float sc = (c ? lam : 1.f) / lsum;
;   float* ex = (float*)shm_raw;
;   if (c == 1) {
; #pragma unroll
;     for (int db = 0; db < 4; ++db)
; #pragma unroll
;       for (int i = 0; i < 16; ++i) ex[(qs * 128 + 32 * db + (i & 3) + 8 * (i >> 2) + 4 * hl) * 32 + r] = O[db][i] * sc;
;   }
;   __syncthreads();
.LBB0_995:
	s_lshl_b32 s0, s26, 14
	s_add_i32 s0, s0, 0
	v_add_u32_e32 v84, s0, v228
	s_waitcnt vmcnt(0)
	s_barrier
	ds_read_b128 v[64:67], v84 offset:49152
	ds_read_b128 v[68:71], v84 offset:53248
	v_add_u32_e32 v85, s0, v227
	v_add_u32_e32 v86, s0, v226
	v_add_u32_e32 v87, s0, v225
	v_cmp_lt_i32_e32 vcc, v206, v205
	s_cmpk_lt_u32 s13, 0x100
	s_waitcnt lgkmcnt(1)
	v_mfma_f32_32x32x16_bf16 v[48:63], v[64:67], v[120:123], v[48:63]
	ds_read_b128 v[64:67], v85 offset:49152
	ds_read_b128 v[72:75], v85 offset:53248
	s_cselect_b64 s[0:1], -1, 0
	s_cmp_eq_u32 s16, 1
	ds_read_b128 v[76:79], v86 offset:53248
	s_waitcnt lgkmcnt(2)
	v_mfma_f32_32x32x16_bf16 v[48:63], v[64:67], v[112:115], v[48:63]
	ds_read_b128 v[64:67], v86 offset:49152
	s_waitcnt lgkmcnt(0)
	v_mfma_f32_32x32x16_bf16 v[48:63], v[64:67], v[124:127], v[48:63]
	ds_read_b128 v[64:67], v87 offset:49152
	ds_read_b128 v[80:83], v87 offset:53248
	v_mfma_f32_32x32x16_bf16 v[32:47], v[68:71], v[120:123], v[32:47]
	s_waitcnt lgkmcnt(1)
	v_mfma_f32_32x32x16_bf16 v[48:63], v[64:67], v[116:119], v[48:63]
	v_mfma_f32_32x32x16_bf16 v[32:47], v[72:75], v[112:115], v[32:47]
	ds_read_b128 v[64:67], v84 offset:57344
	ds_read_b128 v[70:73], v84 offset:61440
	s_waitcnt lgkmcnt(1)
	v_mfma_f32_32x32x16_bf16 v[16:31], v[64:67], v[120:123], v[16:31]
	v_mfma_f32_32x32x16_bf16 v[32:47], v[76:79], v[124:127], v[32:47]
	ds_read_b128 v[64:67], v85 offset:57344
	ds_read_b128 v[74:77], v85 offset:61440
	s_waitcnt lgkmcnt(1)
	v_mfma_f32_32x32x16_bf16 v[16:31], v[64:67], v[112:115], v[16:31]
	v_mfma_f32_32x32x16_bf16 v[32:47], v[80:83], v[116:119], v[32:47]
	ds_read_b128 v[64:67], v86 offset:57344
	ds_read_b128 v[78:81], v86 offset:61440
	v_mfma_f32_32x32x16_bf16 v[0:15], v[70:73], v[120:123], v[0:15]
	s_waitcnt lgkmcnt(1)
	v_mfma_f32_32x32x16_bf16 v[16:31], v[64:67], v[124:127], v[16:31]
	ds_read_b128 v[64:67], v87 offset:57344
	ds_read_b128 v[82:85], v87 offset:61440
	s_waitcnt vmcnt(0)
	s_barrier
	v_mfma_f32_32x32x16_bf16 v[0:15], v[74:77], v[112:115], v[0:15]
	s_waitcnt lgkmcnt(1)
	v_mfma_f32_32x32x16_bf16 v[16:31], v[64:67], v[116:119], v[16:31]
	v_cndmask_b32_e32 v64, v204, v206, vcc
	v_lshlrev_b32_e32 v69, 2, v64
	ds_bpermute_b32 v64, v69, v231
	v_cndmask_b32_e64 v65, v200, 1.0, s[0:1]
	s_waitcnt lgkmcnt(0)
	v_add_f32_e32 v64, v231, v64
	v_mfma_f32_32x32x16_bf16 v[0:15], v[78:81], v[124:127], v[0:15]
	v_div_scale_f32 v66, s[4:5], v64, v64, v65
	v_rcp_f32_e32 v67, v66
	s_nop 0
	v_fma_f32 v68, -v66, v67, 1.0
	v_mfma_f32_32x32x16_bf16 v[0:15], v[82:85], v[116:119], v[0:15]
	v_fmac_f32_e32 v67, v68, v67
	v_div_scale_f32 v68, vcc, v65, v64, v65
	v_mul_f32_e32 v70, v68, v67
	v_fma_f32 v71, -v66, v70, v68
	v_fmac_f32_e32 v70, v71, v67
	v_fma_f32 v66, -v66, v70, v68
	v_div_fmas_f32 v66, v66, v67, v70
	v_div_fixup_f32 v68, v66, v64, v65
	v_lshlrev_b32_e32 v64, 2, v201
	v_lshl_add_u32 v65, v217, 9, 0
	s_cbranch_scc0 .LBB0_997
	s_lshl_b32 s4, s15, 14
	v_mul_f32_e32 v66, v48, v68
	v_add3_u32 v67, v65, v64, s4
	v_mul_f32_e32 v70, v49, v68
	ds_write2_b32 v67, v66, v70 offset1:32
	v_mul_f32_e32 v66, v50, v68
	v_mul_f32_e32 v70, v51, v68
	ds_write2_b32 v67, v66, v70 offset0:64 offset1:96
	v_mul_f32_e32 v66, v52, v68
	v_mul_f32_e32 v70, v53, v68
	v_add_u32_e32 v71, 0x400, v67
	ds_write2_b32 v71, v66, v70 offset1:32
	v_mul_f32_e32 v66, v54, v68
	v_mul_f32_e32 v70, v55, v68
	ds_write2_b32 v71, v66, v70 offset0:64 offset1:96
	v_mul_f32_e32 v66, v56, v68
	v_mul_f32_e32 v70, v57, v68
	v_add_u32_e32 v71, 0x800, v67
	ds_write2_b32 v71, v66, v70 offset1:32
	v_mul_f32_e32 v66, v58, v68
	v_mul_f32_e32 v70, v59, v68
	ds_write2_b32 v71, v66, v70 offset0:64 offset1:96
	v_mul_f32_e32 v66, v60, v68
	v_mul_f32_e32 v70, v61, v68
	v_add_u32_e32 v71, 0xc00, v67
	ds_write2_b32 v71, v66, v70 offset1:32
	v_mul_f32_e32 v66, v62, v68
	v_mul_f32_e32 v70, v63, v68
	ds_write2_b32 v71, v66, v70 offset0:64 offset1:96
	v_mul_f32_e32 v66, v32, v68
	v_mul_f32_e32 v70, v33, v68
	v_add_u32_e32 v71, 0x1000, v67
	ds_write2_b32 v71, v66, v70 offset1:32
	v_mul_f32_e32 v66, v34, v68
	v_mul_f32_e32 v70, v35, v68
	ds_write2_b32 v71, v66, v70 offset0:64 offset1:96
	v_mul_f32_e32 v66, v36, v68
	v_mul_f32_e32 v70, v37, v68
	v_add_u32_e32 v71, 0x1400, v67
	ds_write2_b32 v71, v66, v70 offset1:32
	v_mul_f32_e32 v66, v38, v68
	v_mul_f32_e32 v70, v39, v68
	ds_write2_b32 v71, v66, v70 offset0:64 offset1:96
	v_mul_f32_e32 v66, v40, v68
	v_mul_f32_e32 v70, v41, v68
	v_add_u32_e32 v71, 0x1800, v67
	ds_write2_b32 v71, v66, v70 offset1:32
	v_mul_f32_e32 v66, v42, v68
	v_mul_f32_e32 v70, v43, v68
	ds_write2_b32 v71, v66, v70 offset0:64 offset1:96
	v_mul_f32_e32 v66, v44, v68
	v_mul_f32_e32 v70, v45, v68
	v_add_u32_e32 v71, 0x1c00, v67
	ds_write2_b32 v71, v66, v70 offset1:32
	v_mul_f32_e32 v66, v46, v68
	v_mul_f32_e32 v70, v47, v68
	ds_write2_b32 v71, v66, v70 offset0:64 offset1:96
	v_mul_f32_e32 v66, v16, v68
	v_mul_f32_e32 v70, v17, v68
	v_add_u32_e32 v71, 0x2000, v67
	ds_write2_b32 v71, v66, v70 offset1:32
	v_mul_f32_e32 v66, v18, v68
	v_mul_f32_e32 v70, v19, v68
	ds_write2_b32 v71, v66, v70 offset0:64 offset1:96
	v_mul_f32_e32 v66, v20, v68
	v_mul_f32_e32 v70, v21, v68
	v_add_u32_e32 v71, 0x2400, v67
	ds_write2_b32 v71, v66, v70 offset1:32
	v_mul_f32_e32 v66, v22, v68
	v_mul_f32_e32 v70, v23, v68
	ds_write2_b32 v71, v66, v70 offset0:64 offset1:96
	v_mul_f32_e32 v66, v24, v68
	v_mul_f32_e32 v70, v25, v68
	v_add_u32_e32 v71, 0x2800, v67
	ds_write2_b32 v71, v66, v70 offset1:32
	v_mul_f32_e32 v66, v26, v68
	v_mul_f32_e32 v70, v27, v68
	ds_write2_b32 v71, v66, v70 offset0:64 offset1:96
	v_mul_f32_e32 v66, v28, v68
	v_mul_f32_e32 v70, v29, v68
	v_add_u32_e32 v71, 0x2c00, v67
	ds_write2_b32 v71, v66, v70 offset1:32
	v_mul_f32_e32 v66, v30, v68
	v_mul_f32_e32 v70, v31, v68
	ds_write2_b32 v71, v66, v70 offset0:64 offset1:96
	v_mul_f32_e32 v66, v0, v68
	v_mul_f32_e32 v70, v1, v68
	v_add_u32_e32 v71, 0x3000, v67
	ds_write2_b32 v71, v66, v70 offset1:32
	v_mul_f32_e32 v66, v2, v68
	v_mul_f32_e32 v70, v3, v68
	ds_write2_b32 v71, v66, v70 offset0:64 offset1:96
	v_mul_f32_e32 v66, v4, v68
	v_mul_f32_e32 v70, v5, v68
	v_add_u32_e32 v71, 0x3400, v67
	ds_write2_b32 v71, v66, v70 offset1:32
	v_mul_f32_e32 v66, v6, v68
	v_mul_f32_e32 v70, v7, v68
	ds_write2_b32 v71, v66, v70 offset0:64 offset1:96
	v_mul_f32_e32 v66, v8, v68
	v_mul_f32_e32 v70, v9, v68
	v_add_u32_e32 v71, 0x3800, v67
	ds_write2_b32 v71, v66, v70 offset1:32
	v_mul_f32_e32 v66, v10, v68
	v_mul_f32_e32 v70, v11, v68
	ds_write2_b32 v71, v66, v70 offset0:64 offset1:96
	v_mul_f32_e32 v66, v12, v68
	v_mul_f32_e32 v70, v13, v68
	v_add_u32_e32 v67, 0x3c00, v67
	ds_write2_b32 v67, v66, v70 offset1:32
	v_mul_f32_e32 v66, v14, v68
	v_mul_f32_e32 v70, v15, v68
	ds_write2_b32 v67, v66, v70 offset0:64 offset1:96

; __global__ void __launch_bounds__(512, 2) mega(Params p) {
	.amdhsa_kernel _Z4mega6Params
		.amdhsa_group_segment_fixed_size 0
		.amdhsa_private_segment_fixed_size 0
		.amdhsa_kernarg_size 392
		.amdhsa_user_sgpr_count 2
		.amdhsa_user_sgpr_dispatch_ptr 0
		.amdhsa_user_sgpr_queue_ptr 0
		.amdhsa_user_sgpr_kernarg_segment_ptr 1
		.amdhsa_user_sgpr_dispatch_id 0
		.amdhsa_user_sgpr_kernarg_preload_length 0
		.amdhsa_user_sgpr_kernarg_preload_offset 0
		.amdhsa_user_sgpr_private_segment_size 0
		.amdhsa_uses_dynamic_stack 0
		.amdhsa_enable_private_segment 0
		.amdhsa_system_sgpr_workgroup_id_x 1
		.amdhsa_system_sgpr_workgroup_id_y 0
		.amdhsa_system_sgpr_workgroup_id_z 0
		.amdhsa_system_sgpr_workgroup_info 0
		.amdhsa_system_vgpr_workitem_id 2
		.amdhsa_next_free_vgpr 252
		.amdhsa_next_free_sgpr 102
		.amdhsa_accum_offset 252
		.amdhsa_reserve_vcc 1
		.amdhsa_float_round_mode_32 0
		.amdhsa_float_round_mode_16_64 0
		.amdhsa_float_denorm_mode_32 3
		.amdhsa_float_denorm_mode_16_64 3
		.amdhsa_dx10_clamp 1
		.amdhsa_ieee_mode 1
		.amdhsa_fp16_overflow 0
		.amdhsa_tg_split 0
		.amdhsa_exception_fp_ieee_invalid_op 0
		.amdhsa_exception_fp_denorm_src 0
		.amdhsa_exception_fp_ieee_div_zero 0
		.amdhsa_exception_fp_ieee_overflow 0
		.amdhsa_exception_fp_ieee_underflow 0
		.amdhsa_exception_fp_ieee_inexact 0
		.amdhsa_exception_int_div_zero 0
	.end_amdhsa_kernel

; __global__ void __launch_bounds__(512, 2) mega(Params p) {
amdhsa.kernels:
  - .agpr_count:     0
    .args:
      - .offset:         0
        .size:           136
        .value_kind:     by_value
      - .offset:         136
        .size:           4
        .value_kind:     hidden_block_count_x
      - .offset:         140
        .size:           4
        .value_kind:     hidden_block_count_y
      - .offset:         144
        .size:           4
        .value_kind:     hidden_block_count_z
      - .offset:         148
        .size:           2
        .value_kind:     hidden_group_size_x
      - .offset:         150
        .size:           2
        .value_kind:     hidden_group_size_y
      - .offset:         152
        .size:           2
        .value_kind:     hidden_group_size_z
      - .offset:         154
        .size:           2
        .value_kind:     hidden_remainder_x
      - .offset:         156
        .size:           2
        .value_kind:     hidden_remainder_y
      - .offset:         158
        .size:           2
        .value_kind:     hidden_remainder_z
      - .offset:         176
        .size:           8
        .value_kind:     hidden_global_offset_x
      - .offset:         184
        .size:           8
        .value_kind:     hidden_global_offset_y
      - .offset:         192
        .size:           8
        .value_kind:     hidden_global_offset_z
      - .offset:         200
        .size:           2
        .value_kind:     hidden_grid_dims
      - .offset:         224
        .size:           8
        .value_kind:     hidden_multigrid_sync_arg
      - .offset:         256
        .size:           4
        .value_kind:     hidden_dynamic_lds_size
    .group_segment_fixed_size: 0
    .kernarg_segment_align: 8
    .kernarg_segment_size: 392
    .language:       OpenCL C
    .language_version:
      - 2
      - 0
    .max_flat_workgroup_size: 512
    .name:           _Z4mega6Params
    .private_segment_fixed_size: 0
    .sgpr_count:     108
    .sgpr_spill_count: 20
    .symbol:         _Z4mega6Params.kd
    .uniform_work_group_size: 1
    .uses_dynamic_stack: false
    .vgpr_count:     252
    .vgpr_spill_count: 0
    .wavefront_size: 64
